# v75 + attention: K/V prefetch addresses advanced incrementally per tile instead of rebuilt with 64-bit multiplies
# baseline (speedup 1.0000x reference)
.LBB0_335:
	s_and_b64 s[14:15], s[4:5], exec
	s_cselect_b32 s8, 1, 4
	s_cselect_b32 s0, s1, s0
	s_lshr_b32 s1, s12, s8
	s_and_b32 s1, s1, 3
	s_lshl_b32 s8, s1, 2
	v_readlane_b32 s12, v254, 44
	s_add_i32 s14, s8, s12
	s_lshl_b32 s12, s14, 6
	s_mov_b32 s8, s12
	s_and_b32 s16, s12, 0xffffff00
	v_writelane_b32 v255, s8, 6
	s_ashr_i32 s17, s16, 31
	s_lshl_b64 s[16:17], s[16:17], 1
	v_writelane_b32 v255, s9, 7
	v_readlane_b32 s8, v254, 45
	s_add_u32 s16, s8, s16
	v_readlane_b32 s8, v254, 46
	s_addc_u32 s17, s8, s17
	v_lshl_add_u64 v[188:189], s[70:71], 0, v[168:169]
	v_mov_b64_e32 v[0:1], s[16:17]
	v_mad_u64_u32 v[0:1], s[16:17], v188, s33, v[0:1]
	v_mov_b32_e32 v2, v1
	v_mad_u64_u32 v[2:3], s[16:17], v189, s33, v[2:3]
	v_mov_b32_e32 v1, v2
	v_lshl_add_u64 v[0:1], v[0:1], 0, v[176:177]
	s_mov_b64 s[16:17], 0x18000
	s_mov_b32 s8, 0x18000
	global_load_dwordx4 v[128:131], v[0:1], off
	global_load_dwordx4 v[132:135], v[0:1], off offset:32
	global_load_dwordx4 v[136:139], v[0:1], off offset:256
	global_load_dwordx4 v[140:143], v[0:1], off offset:288
	v_lshl_add_u64 v[2:3], v[0:1], 0, s[16:17]
	v_add_co_u32_e32 v0, vcc, s8, v0
	s_lshl_b32 s8, s11, 1
	s_sub_i32 s11, 2, s8
	s_sub_i32 s8, 33, s8
	s_max_i32 s16, s11, 0
	s_min_u32 s8, s8, 5
	s_sub_i32 s8, s8, s16
	s_add_i32 s8, s8, 5
	s_and_b64 s[4:5], s[4:5], exec
	s_cselect_b32 s11, 4, s8
	s_add_u32 s6, s6, 0x10000
	v_readlane_b32 s72, v254, 16
	s_addc_u32 s7, s7, 0
	s_ashr_i32 s15, s14, 31
	v_readlane_b32 s82, v254, 26
	v_readlane_b32 s83, v254, 27
	s_lshl_b32 s17, s1, 5
	s_lshl_b32 s4, s1, 6
	s_lshl_b64 s[14:15], s[14:15], 2
	s_mov_b64 s[70:71], s[82:83]
	s_add_u32 s14, s70, s14
	v_addc_co_u32_e32 v1, vcc, 0, v1, vcc
	s_addc_u32 s15, s71, s15
	global_load_dwordx4 v[144:147], v[2:3], off offset:32
	global_load_dwordx4 v[148:151], v[2:3], off offset:256
	global_load_dwordx4 v[152:155], v[0:1], off
	global_load_dwordx4 v[156:159], v[2:3], off offset:288
	global_load_dword v64, v173, s[14:15]
	v_lshl_add_u64 v[0:1], s[6:7], 0, v[170:171]
	v_mad_u64_u32 v[2:3], s[14:15], v0, s33, v[178:179]
	v_mov_b32_e32 v0, v3
	v_mad_u64_u32 v[0:1], s[14:15], v1, s33, v[0:1]
	v_mov_b32_e32 v3, v0
	s_lshl_b32 s8, s1, 7
	s_mov_b32 s5, s9
	v_lshl_add_u64 v[0:1], v[2:3], 0, s[8:9]
	v_lshl_add_u64 v[2:3], v[2:3], 0, v[172:173]
	v_lshl_add_u64 v[0:1], v[0:1], 0, v[182:183]
	v_lshl_add_u64 v[2:3], v[2:3], 0, s[4:5]
	v_lshl_add_u64 v[2:3], v[2:3], 0, v[186:187]
	global_load_dwordx4 v[160:163], v[0:1], off offset:2560
	global_load_dwordx4 v[164:167], v[2:3], off offset:2048
	v_mov_b32_e32 v250, v2
	v_mov_b32_e32 v251, v3
	v_mov_b32_e32 v252, v0
	v_mov_b32_e32 v253, v1
	s_ashr_i32 s1, s0, 31
	s_lshl_b64 s[0:1], s[0:1], 11
	s_or_b32 s0, s0, s13
	s_add_u32 s13, s0, 0xffffff80
	s_addc_u32 s14, s1, -1
	s_lshl_b32 s16, s16, 6
	v_readlane_b32 s0, v255, 4
	s_add_i32 s15, s0, s16
	v_readlane_b32 s0, v254, 47
	v_mov_b32_e32 v48, v173
	v_mov_b32_e32 v49, v173
	v_readlane_b32 s1, v254, 48
	v_mov_b32_e32 v50, v173
	v_mov_b32_e32 v51, v173
	v_mov_b32_e32 v52, v173
	v_mov_b32_e32 v53, v173
	v_mov_b32_e32 v54, v173
	v_mov_b32_e32 v55, v173
	v_mov_b32_e32 v56, v173
	v_mov_b32_e32 v57, v173
	v_mov_b32_e32 v58, v173
	v_mov_b32_e32 v59, v173
	v_mov_b32_e32 v60, v173
	v_mov_b32_e32 v61, v173
	v_mov_b32_e32 v62, v173
	v_mov_b32_e32 v63, v173
	v_mov_b64_e32 v[16:17], v[48:49]
	v_mov_b64_e32 v[32:33], v[48:49]
	v_mov_b64_e32 v[0:1], v[48:49]
	s_mov_b32 s12, 0
	v_mov_b64_e32 v[18:19], v[50:51]
	v_mov_b64_e32 v[20:21], v[52:53]
	v_mov_b64_e32 v[22:23], v[54:55]
	v_mov_b64_e32 v[24:25], v[56:57]
	v_mov_b64_e32 v[26:27], v[58:59]
	v_mov_b64_e32 v[28:29], v[60:61]
	v_mov_b64_e32 v[30:31], v[62:63]
	v_mov_b64_e32 v[34:35], v[50:51]
	v_mov_b64_e32 v[36:37], v[52:53]
	v_mov_b64_e32 v[38:39], v[54:55]
	v_mov_b64_e32 v[40:41], v[56:57]
	v_mov_b64_e32 v[42:43], v[58:59]
	v_mov_b64_e32 v[44:45], v[60:61]
	v_mov_b64_e32 v[46:47], v[62:63]
	v_mov_b64_e32 v[2:3], v[50:51]
	v_mov_b64_e32 v[4:5], v[52:53]
	v_mov_b64_e32 v[6:7], v[54:55]
	v_mov_b64_e32 v[8:9], v[56:57]
	v_mov_b64_e32 v[10:11], v[58:59]
	v_mov_b64_e32 v[12:13], v[60:61]
	v_mov_b64_e32 v[14:15], v[62:63]
	s_lshl_b32 s8, s17, 1
	s_lshl_b32 s4, s4, 1
	s_addk_i32 s16, 0xff40
	s_mov_b32 s72, 0
	v_readlane_b32 s73, v254, 17
	v_readlane_b32 s74, v254, 18
	v_readlane_b32 s75, v254, 19
	v_readlane_b32 s76, v254, 20
	v_readlane_b32 s77, v254, 21
	v_readlane_b32 s78, v254, 22
	v_readlane_b32 s79, v254, 23
	v_readlane_b32 s80, v254, 24
	v_readlane_b32 s81, v254, 25
	s_waitcnt vmcnt(2)
	v_mul_f32_e32 v64, 0x3fb8aa3b, v64
	v_exp_f32_e32 v64, v64
	v_readlane_b32 s84, v254, 28
	v_readlane_b32 s85, v254, 29
	v_readlane_b32 s86, v254, 30
	v_cndmask_b32_e64 v190, 0, v64, s[0:1]
	v_mov_b32_e32 v191, v190
	v_readlane_b32 s87, v254, 31

.LBB0_341:
	s_cmp_eq_u32 s72, 3
	s_cbranch_scc1 .Lai_full
	v_add_co_u32_e32 v250, vcc, 0x30000, v250
	v_addc_co_u32_e32 v251, vcc, 0, v251, vcc
	v_add_co_u32_e32 v252, vcc, 0x30000, v252
	v_addc_co_u32_e32 v253, vcc, 0, v253, vcc
	s_branch .Lai_ld
.Lai_full:
	v_lshl_add_u64 v[64:65], s[0:1], 0, v[170:171]
	v_mov_b64_e32 v[66:67], s[2:3]
	v_mad_u64_u32 v[66:67], s[0:1], v64, s33, v[66:67]
	v_mov_b32_e32 v64, v67
	v_mad_u64_u32 v[64:65], s[0:1], v65, s33, v[64:65]
	v_mov_b32_e32 v67, v64
	v_lshl_add_u64 v[64:65], v[66:67], 0, v[172:173]
	v_lshl_add_u64 v[64:65], v[64:65], 0, s[8:9]
	v_mov_b32_e32 v185, v173
	s_mov_b32 s5, s9
	v_lshl_add_u64 v[64:65], v[64:65], 0, v[184:185]
	v_lshl_add_u64 v[66:67], v[66:67], 0, s[4:5]
	v_mov_b32_e32 v181, v173
	v_lshl_add_u64 v[66:67], v[66:67], 0, v[180:181]
	v_mov_b32_e32 v250, v64
	v_mov_b32_e32 v251, v65
	v_mov_b32_e32 v252, v66
	v_mov_b32_e32 v253, v67
.Lai_ld:
	global_load_dwordx4 v[164:167], v[250:251], off offset:2048
	global_load_dwordx4 v[160:163], v[252:253], off offset:2560
